# consolidated version with rolling (16-in-flight) slab loads in the split-K exchange consumer
# speedup vs baseline: 1.0035x; 1.0032x over previous
; template <int l>
; __device__ __forceinline__ void run_layer(LAS unsigned char* lds, unsigned char* ws_in, float* out_in, const float* x_p, const float* x_s, const PIn* pin, const int G, const int bid, const int wave) {
;     ...
;             pg8::RowOrder<DM / 256> S; S.init(G, bid);
;             EpiRes E{ws, out, nullptr, nullptr, 0, -1};
;             pg8::gemm_phase<FF, EpiRes, pg8::RowOrder<DM / 256>>(lds, ACT, (const bf16*)(wb + W_D), S, E, wave);
.Lp5a_go2:
.Lp5a_poll3:
	global_load_dword v142, v141, s[44:45] offset:3212 sc1
	s_waitcnt vmcnt(0)
	v_readfirstlane_b32 s82, v142
	s_nop 0
	s_cmp_ge_u32 s82, 8
	s_cbranch_scc1 .Lp5a_go3
	s_sleep 1
	s_branch .Lp5a_poll3
.Lp5a_go3:
.Lp5a_poll1:
	global_load_dword v142, v141, s[44:45] offset:3204 sc1
	s_waitcnt vmcnt(0)
	v_readfirstlane_b32 s82, v142
	s_nop 0
	s_cmp_ge_u32 s82, 8
	s_cbranch_scc1 .Lp5a_go1
	s_sleep 1
	s_branch .Lp5a_poll1
.Lp5a_go1:
	s_add_u32 s78, s76, 0x40000
	s_addc_u32 s79, s77, 0
	global_load_dwordx4 v[200:203], v140, s[78:79] sc0 sc1
	s_add_u32 s78, s78, 0x2000
	s_addc_u32 s79, s79, 0
	global_load_dwordx4 v[204:207], v140, s[78:79] sc0 sc1
	s_add_u32 s78, s78, 0x2000
	s_addc_u32 s79, s79, 0
	global_load_dwordx4 v[208:211], v140, s[78:79] sc0 sc1
	s_add_u32 s78, s78, 0x2000
	s_addc_u32 s79, s79, 0
	global_load_dwordx4 v[212:215], v140, s[78:79] sc0 sc1
	s_add_u32 s78, s78, 0x2000
	s_addc_u32 s79, s79, 0
	global_load_dwordx4 v[216:219], v140, s[78:79] sc0 sc1
	s_add_u32 s78, s78, 0x2000
	s_addc_u32 s79, s79, 0
	global_load_dwordx4 v[220:223], v140, s[78:79] sc0 sc1
	s_add_u32 s78, s78, 0x2000
	s_addc_u32 s79, s79, 0
	global_load_dwordx4 v[224:227], v140, s[78:79] sc0 sc1
	s_add_u32 s78, s78, 0x2000
	s_addc_u32 s79, s79, 0
	global_load_dwordx4 v[228:231], v140, s[78:79] sc0 sc1
	s_add_u32 s78, s78, 0x2000
	s_addc_u32 s79, s79, 0
	global_load_dwordx4 v[232:235], v140, s[78:79] sc0 sc1
	s_add_u32 s78, s78, 0x2000
	s_addc_u32 s79, s79, 0
	global_load_dwordx4 v[236:239], v140, s[78:79] sc0 sc1
	s_add_u32 s78, s78, 0x2000
	s_addc_u32 s79, s79, 0
	global_load_dwordx4 v[240:243], v140, s[78:79] sc0 sc1
	s_add_u32 s78, s78, 0x2000
	s_addc_u32 s79, s79, 0
	global_load_dwordx4 v[244:247], v140, s[78:79] sc0 sc1
	s_add_u32 s78, s78, 0x2000
	s_addc_u32 s79, s79, 0
	global_load_dwordx4 v[160:163], v140, s[78:79] sc0 sc1
	s_add_u32 s78, s78, 0x2000
	s_addc_u32 s79, s79, 0
	global_load_dwordx4 v[164:167], v140, s[78:79] sc0 sc1
	s_add_u32 s78, s78, 0x2000
	s_addc_u32 s79, s79, 0
	global_load_dwordx4 v[168:171], v140, s[78:79] sc0 sc1
	s_add_u32 s78, s78, 0x2000
	s_addc_u32 s79, s79, 0
	global_load_dwordx4 v[172:175], v140, s[78:79] sc0 sc1
	s_waitcnt vmcnt(15)
	v_pk_add_f32 v[0:1], v[0:1], v[200:201]
	v_pk_add_f32 v[2:3], v[2:3], v[202:203]
	s_add_u32 s78, s78, 0x2000
	s_addc_u32 s79, s79, 0
	global_load_dwordx4 v[200:203], v140, s[78:79] sc0 sc1
	s_waitcnt vmcnt(15)
	v_pk_add_f32 v[4:5], v[4:5], v[204:205]
	v_pk_add_f32 v[6:7], v[6:7], v[206:207]
	s_add_u32 s78, s78, 0x2000
	s_addc_u32 s79, s79, 0
	global_load_dwordx4 v[204:207], v140, s[78:79] sc0 sc1
	s_waitcnt vmcnt(15)
	v_pk_add_f32 v[8:9], v[8:9], v[208:209]
	v_pk_add_f32 v[10:11], v[10:11], v[210:211]
	s_add_u32 s78, s78, 0x2000
	s_addc_u32 s79, s79, 0
	global_load_dwordx4 v[208:211], v140, s[78:79] sc0 sc1
	s_waitcnt vmcnt(15)
	v_pk_add_f32 v[12:13], v[12:13], v[212:213]
	v_pk_add_f32 v[14:15], v[14:15], v[214:215]
	s_add_u32 s78, s78, 0x2000
	s_addc_u32 s79, s79, 0
	global_load_dwordx4 v[212:215], v140, s[78:79] sc0 sc1
	s_waitcnt vmcnt(15)
	v_pk_add_f32 v[16:17], v[16:17], v[216:217]
	v_pk_add_f32 v[18:19], v[18:19], v[218:219]
	s_add_u32 s78, s78, 0x2000
	s_addc_u32 s79, s79, 0
	global_load_dwordx4 v[216:219], v140, s[78:79] sc0 sc1
	s_waitcnt vmcnt(15)
	v_pk_add_f32 v[20:21], v[20:21], v[220:221]
	v_pk_add_f32 v[22:23], v[22:23], v[222:223]
	s_add_u32 s78, s78, 0x2000
	s_addc_u32 s79, s79, 0
	global_load_dwordx4 v[220:223], v140, s[78:79] sc0 sc1
	s_waitcnt vmcnt(15)
	v_pk_add_f32 v[24:25], v[24:25], v[224:225]
	v_pk_add_f32 v[26:27], v[26:27], v[226:227]
	s_add_u32 s78, s78, 0x2000
	s_addc_u32 s79, s79, 0
	global_load_dwordx4 v[224:227], v140, s[78:79] sc0 sc1
	s_waitcnt vmcnt(15)
	v_pk_add_f32 v[28:29], v[28:29], v[228:229]
	v_pk_add_f32 v[30:31], v[30:31], v[230:231]
	s_add_u32 s78, s78, 0x2000
	s_addc_u32 s79, s79, 0
	global_load_dwordx4 v[228:231], v140, s[78:79] sc0 sc1
	s_waitcnt vmcnt(15)
	v_pk_add_f32 v[32:33], v[32:33], v[232:233]
	v_pk_add_f32 v[34:35], v[34:35], v[234:235]
	s_add_u32 s78, s78, 0x2000
	s_addc_u32 s79, s79, 0
	global_load_dwordx4 v[232:235], v140, s[78:79] sc0 sc1
	s_waitcnt vmcnt(15)
	v_pk_add_f32 v[36:37], v[36:37], v[236:237]
	v_pk_add_f32 v[38:39], v[38:39], v[238:239]
	s_add_u32 s78, s78, 0x2000
	s_addc_u32 s79, s79, 0
	global_load_dwordx4 v[236:239], v140, s[78:79] sc0 sc1
	s_waitcnt vmcnt(15)
	v_pk_add_f32 v[40:41], v[40:41], v[240:241]
	v_pk_add_f32 v[42:43], v[42:43], v[242:243]
	s_add_u32 s78, s78, 0x2000
	s_addc_u32 s79, s79, 0
	global_load_dwordx4 v[240:243], v140, s[78:79] sc0 sc1
	s_waitcnt vmcnt(15)
	v_pk_add_f32 v[44:45], v[44:45], v[244:245]
	v_pk_add_f32 v[46:47], v[46:47], v[246:247]
	s_add_u32 s78, s78, 0x2000
	s_addc_u32 s79, s79, 0
	global_load_dwordx4 v[244:247], v140, s[78:79] sc0 sc1
	s_waitcnt vmcnt(15)
	v_pk_add_f32 v[48:49], v[48:49], v[160:161]
	v_pk_add_f32 v[50:51], v[50:51], v[162:163]
	s_add_u32 s78, s78, 0x2000
	s_addc_u32 s79, s79, 0
	global_load_dwordx4 v[160:163], v140, s[78:79] sc0 sc1
	s_waitcnt vmcnt(15)
	v_pk_add_f32 v[52:53], v[52:53], v[164:165]
	v_pk_add_f32 v[54:55], v[54:55], v[166:167]
	s_add_u32 s78, s78, 0x2000
	s_addc_u32 s79, s79, 0
	global_load_dwordx4 v[164:167], v140, s[78:79] sc0 sc1
	s_waitcnt vmcnt(15)
	v_pk_add_f32 v[56:57], v[56:57], v[168:169]
	v_pk_add_f32 v[58:59], v[58:59], v[170:171]
	s_add_u32 s78, s78, 0x2000
	s_addc_u32 s79, s79, 0
	global_load_dwordx4 v[168:171], v140, s[78:79] sc0 sc1
	s_waitcnt vmcnt(15)
	v_pk_add_f32 v[60:61], v[60:61], v[172:173]
	v_pk_add_f32 v[62:63], v[62:63], v[174:175]
	s_add_u32 s78, s78, 0x2000
	s_addc_u32 s79, s79, 0
	global_load_dwordx4 v[172:175], v140, s[78:79] sc0 sc1
	s_waitcnt vmcnt(15)
; template <int l>
; __device__ __forceinline__ void run_layer(LAS unsigned char* lds, unsigned char* ws_in, float* out_in, const float* x_p, const float* x_s, const PIn* pin, const int G, const int bid, const int wave) {
;     ...
;             pg8::RowOrder<DM / 256> S; S.init(G, bid);
;             EpiRes E{ws, out, nullptr, nullptr, 0, -1};
;             pg8::gemm_phase<FF, EpiRes, pg8::RowOrder<DM / 256>>(lds, ACT, (const bf16*)(wb + W_D), S, E, wave);
	v_pk_add_f32 v[64:65], v[64:65], v[200:201]
	v_pk_add_f32 v[66:67], v[66:67], v[202:203]
	s_add_u32 s78, s76, 0x80000
	s_addc_u32 s79, s77, 0
	global_load_dwordx4 v[200:203], v140, s[78:79] sc0 sc1
	s_waitcnt vmcnt(15)
	v_pk_add_f32 v[68:69], v[68:69], v[204:205]
	v_pk_add_f32 v[70:71], v[70:71], v[206:207]
	s_add_u32 s78, s78, 0x2000
	s_addc_u32 s79, s79, 0
	global_load_dwordx4 v[204:207], v140, s[78:79] sc0 sc1
	s_waitcnt vmcnt(15)
	v_pk_add_f32 v[72:73], v[72:73], v[208:209]
	v_pk_add_f32 v[74:75], v[74:75], v[210:211]
	s_add_u32 s78, s78, 0x2000
	s_addc_u32 s79, s79, 0
	global_load_dwordx4 v[208:211], v140, s[78:79] sc0 sc1
	s_waitcnt vmcnt(15)
	v_pk_add_f32 v[76:77], v[76:77], v[212:213]
	v_pk_add_f32 v[78:79], v[78:79], v[214:215]
	s_add_u32 s78, s78, 0x2000
	s_addc_u32 s79, s79, 0
	global_load_dwordx4 v[212:215], v140, s[78:79] sc0 sc1
	s_waitcnt vmcnt(15)
	v_pk_add_f32 v[80:81], v[80:81], v[216:217]
	v_pk_add_f32 v[82:83], v[82:83], v[218:219]
	s_add_u32 s78, s78, 0x2000
	s_addc_u32 s79, s79, 0
	global_load_dwordx4 v[216:219], v140, s[78:79] sc0 sc1
	s_waitcnt vmcnt(15)
	v_pk_add_f32 v[84:85], v[84:85], v[220:221]
	v_pk_add_f32 v[86:87], v[86:87], v[222:223]
	s_add_u32 s78, s78, 0x2000
	s_addc_u32 s79, s79, 0
	global_load_dwordx4 v[220:223], v140, s[78:79] sc0 sc1
	s_waitcnt vmcnt(15)
	v_pk_add_f32 v[88:89], v[88:89], v[224:225]
	v_pk_add_f32 v[90:91], v[90:91], v[226:227]
	s_add_u32 s78, s78, 0x2000
	s_addc_u32 s79, s79, 0
	global_load_dwordx4 v[224:227], v140, s[78:79] sc0 sc1
	s_waitcnt vmcnt(15)
	v_pk_add_f32 v[92:93], v[92:93], v[228:229]
	v_pk_add_f32 v[94:95], v[94:95], v[230:231]
	s_add_u32 s78, s78, 0x2000
	s_addc_u32 s79, s79, 0
	global_load_dwordx4 v[228:231], v140, s[78:79] sc0 sc1
	s_waitcnt vmcnt(15)
	v_pk_add_f32 v[96:97], v[96:97], v[232:233]
	v_pk_add_f32 v[98:99], v[98:99], v[234:235]
	s_add_u32 s78, s78, 0x2000
	s_addc_u32 s79, s79, 0
	global_load_dwordx4 v[232:235], v140, s[78:79] sc0 sc1
	s_waitcnt vmcnt(15)
	v_pk_add_f32 v[100:101], v[100:101], v[236:237]
	v_pk_add_f32 v[102:103], v[102:103], v[238:239]
	s_add_u32 s78, s78, 0x2000
	s_addc_u32 s79, s79, 0
	global_load_dwordx4 v[236:239], v140, s[78:79] sc0 sc1
	s_waitcnt vmcnt(15)
	v_pk_add_f32 v[104:105], v[104:105], v[240:241]
	v_pk_add_f32 v[106:107], v[106:107], v[242:243]
	s_add_u32 s78, s78, 0x2000
	s_addc_u32 s79, s79, 0
	global_load_dwordx4 v[240:243], v140, s[78:79] sc0 sc1
	s_waitcnt vmcnt(15)
	v_pk_add_f32 v[108:109], v[108:109], v[244:245]
	v_pk_add_f32 v[110:111], v[110:111], v[246:247]
	s_add_u32 s78, s78, 0x2000
	s_addc_u32 s79, s79, 0
	global_load_dwordx4 v[244:247], v140, s[78:79] sc0 sc1
	s_waitcnt vmcnt(15)
	v_pk_add_f32 v[112:113], v[112:113], v[160:161]
	v_pk_add_f32 v[114:115], v[114:115], v[162:163]
	s_add_u32 s78, s78, 0x2000
	s_addc_u32 s79, s79, 0
	global_load_dwordx4 v[160:163], v140, s[78:79] sc0 sc1
	s_waitcnt vmcnt(15)
	v_pk_add_f32 v[116:117], v[116:117], v[164:165]
	v_pk_add_f32 v[118:119], v[118:119], v[166:167]
	s_add_u32 s78, s78, 0x2000
	s_addc_u32 s79, s79, 0
	global_load_dwordx4 v[164:167], v140, s[78:79] sc0 sc1
	s_waitcnt vmcnt(15)
	v_pk_add_f32 v[120:121], v[120:121], v[168:169]
	v_pk_add_f32 v[122:123], v[122:123], v[170:171]
	s_add_u32 s78, s78, 0x2000
	s_addc_u32 s79, s79, 0
	global_load_dwordx4 v[168:171], v140, s[78:79] sc0 sc1
	s_waitcnt vmcnt(15)
	v_pk_add_f32 v[124:125], v[124:125], v[172:173]
	v_pk_add_f32 v[126:127], v[126:127], v[174:175]
	s_add_u32 s78, s78, 0x2000
	s_addc_u32 s79, s79, 0
	global_load_dwordx4 v[172:175], v140, s[78:79] sc0 sc1
	s_waitcnt vmcnt(15)
	v_pk_add_f32 v[0:1], v[0:1], v[200:201]
	v_pk_add_f32 v[2:3], v[2:3], v[202:203]
	s_add_u32 s78, s78, 0x2000
	s_addc_u32 s79, s79, 0
	global_load_dwordx4 v[200:203], v140, s[78:79] sc0 sc1
	s_waitcnt vmcnt(15)
	v_pk_add_f32 v[4:5], v[4:5], v[204:205]
	v_pk_add_f32 v[6:7], v[6:7], v[206:207]
	s_add_u32 s78, s78, 0x2000
	s_addc_u32 s79, s79, 0
	global_load_dwordx4 v[204:207], v140, s[78:79] sc0 sc1
	s_waitcnt vmcnt(15)
	v_pk_add_f32 v[8:9], v[8:9], v[208:209]
	v_pk_add_f32 v[10:11], v[10:11], v[210:211]
	s_add_u32 s78, s78, 0x2000
	s_addc_u32 s79, s79, 0
	global_load_dwordx4 v[208:211], v140, s[78:79] sc0 sc1
	s_waitcnt vmcnt(15)
	v_pk_add_f32 v[12:13], v[12:13], v[212:213]
	v_pk_add_f32 v[14:15], v[14:15], v[214:215]
	s_add_u32 s78, s78, 0x2000
	s_addc_u32 s79, s79, 0
	global_load_dwordx4 v[212:215], v140, s[78:79] sc0 sc1
	s_waitcnt vmcnt(15)
	v_pk_add_f32 v[16:17], v[16:17], v[216:217]
	v_pk_add_f32 v[18:19], v[18:19], v[218:219]
	s_add_u32 s78, s78, 0x2000
	s_addc_u32 s79, s79, 0
	global_load_dwordx4 v[216:219], v140, s[78:79] sc0 sc1
	s_waitcnt vmcnt(15)
	v_pk_add_f32 v[20:21], v[20:21], v[220:221]
	v_pk_add_f32 v[22:23], v[22:23], v[222:223]
	s_add_u32 s78, s78, 0x2000
	s_addc_u32 s79, s79, 0
	global_load_dwordx4 v[220:223], v140, s[78:79] sc0 sc1
	s_waitcnt vmcnt(15)
	v_pk_add_f32 v[24:25], v[24:25], v[224:225]
	v_pk_add_f32 v[26:27], v[26:27], v[226:227]
	s_add_u32 s78, s78, 0x2000
	s_addc_u32 s79, s79, 0
	global_load_dwordx4 v[224:227], v140, s[78:79] sc0 sc1
	s_waitcnt vmcnt(15)
	v_pk_add_f32 v[28:29], v[28:29], v[228:229]
	v_pk_add_f32 v[30:31], v[30:31], v[230:231]
	s_add_u32 s78, s78, 0x2000
	s_addc_u32 s79, s79, 0
	global_load_dwordx4 v[228:231], v140, s[78:79] sc0 sc1
	s_waitcnt vmcnt(15)
	v_pk_add_f32 v[32:33], v[32:33], v[232:233]
	v_pk_add_f32 v[34:35], v[34:35], v[234:235]
	s_add_u32 s78, s78, 0x2000
	s_addc_u32 s79, s79, 0
	global_load_dwordx4 v[232:235], v140, s[78:79] sc0 sc1
	s_waitcnt vmcnt(15)
	v_pk_add_f32 v[36:37], v[36:37], v[236:237]
	v_pk_add_f32 v[38:39], v[38:39], v[238:239]
	s_add_u32 s78, s78, 0x2000
	s_addc_u32 s79, s79, 0
	global_load_dwordx4 v[236:239], v140, s[78:79] sc0 sc1
	s_waitcnt vmcnt(15)
; template <int l>
; __device__ __forceinline__ void run_layer(LAS unsigned char* lds, unsigned char* ws_in, float* out_in, const float* x_p, const float* x_s, const PIn* pin, const int G, const int bid, const int wave) {
;     ...
;             pg8::RowOrder<DM / 256> S; S.init(G, bid);
;             EpiRes E{ws, out, nullptr, nullptr, 0, -1};
;             pg8::gemm_phase<FF, EpiRes, pg8::RowOrder<DM / 256>>(lds, ACT, (const bf16*)(wb + W_D), S, E, wave);
	v_pk_add_f32 v[40:41], v[40:41], v[240:241]
	v_pk_add_f32 v[42:43], v[42:43], v[242:243]
	s_add_u32 s78, s78, 0x2000
	s_addc_u32 s79, s79, 0
	global_load_dwordx4 v[240:243], v140, s[78:79] sc0 sc1
	s_waitcnt vmcnt(15)
	v_pk_add_f32 v[44:45], v[44:45], v[244:245]
	v_pk_add_f32 v[46:47], v[46:47], v[246:247]
	s_add_u32 s78, s78, 0x2000
	s_addc_u32 s79, s79, 0
	global_load_dwordx4 v[244:247], v140, s[78:79] sc0 sc1
	s_waitcnt vmcnt(15)
	v_pk_add_f32 v[48:49], v[48:49], v[160:161]
	v_pk_add_f32 v[50:51], v[50:51], v[162:163]
	s_add_u32 s78, s78, 0x2000
	s_addc_u32 s79, s79, 0
	global_load_dwordx4 v[160:163], v140, s[78:79] sc0 sc1
	s_waitcnt vmcnt(15)
	v_pk_add_f32 v[52:53], v[52:53], v[164:165]
	v_pk_add_f32 v[54:55], v[54:55], v[166:167]
	s_add_u32 s78, s78, 0x2000
	s_addc_u32 s79, s79, 0
	global_load_dwordx4 v[164:167], v140, s[78:79] sc0 sc1
	s_waitcnt vmcnt(15)
	v_pk_add_f32 v[56:57], v[56:57], v[168:169]
	v_pk_add_f32 v[58:59], v[58:59], v[170:171]
	s_add_u32 s78, s78, 0x2000
	s_addc_u32 s79, s79, 0
	global_load_dwordx4 v[168:171], v140, s[78:79] sc0 sc1
	s_waitcnt vmcnt(15)
	v_pk_add_f32 v[60:61], v[60:61], v[172:173]
	v_pk_add_f32 v[62:63], v[62:63], v[174:175]
	s_add_u32 s78, s78, 0x2000
	s_addc_u32 s79, s79, 0
	global_load_dwordx4 v[172:175], v140, s[78:79] sc0 sc1
	s_waitcnt vmcnt(15)
	v_pk_add_f32 v[64:65], v[64:65], v[200:201]
	v_pk_add_f32 v[66:67], v[66:67], v[202:203]
	s_add_u32 s78, s76, 0x0
	s_addc_u32 s79, s77, 0
	global_load_dwordx4 v[200:203], v140, s[78:79] sc0 sc1
	s_waitcnt vmcnt(15)
	v_pk_add_f32 v[68:69], v[68:69], v[204:205]
	v_pk_add_f32 v[70:71], v[70:71], v[206:207]
	s_add_u32 s78, s78, 0x2000
	s_addc_u32 s79, s79, 0
	global_load_dwordx4 v[204:207], v140, s[78:79] sc0 sc1
	s_waitcnt vmcnt(15)
	v_pk_add_f32 v[72:73], v[72:73], v[208:209]
	v_pk_add_f32 v[74:75], v[74:75], v[210:211]
	s_add_u32 s78, s78, 0x2000
	s_addc_u32 s79, s79, 0
	global_load_dwordx4 v[208:211], v140, s[78:79] sc0 sc1
	s_waitcnt vmcnt(15)
	v_pk_add_f32 v[76:77], v[76:77], v[212:213]
	v_pk_add_f32 v[78:79], v[78:79], v[214:215]
	s_add_u32 s78, s78, 0x2000
	s_addc_u32 s79, s79, 0
	global_load_dwordx4 v[212:215], v140, s[78:79] sc0 sc1
	s_waitcnt vmcnt(15)
	v_pk_add_f32 v[80:81], v[80:81], v[216:217]
	v_pk_add_f32 v[82:83], v[82:83], v[218:219]
	s_add_u32 s78, s78, 0x2000
	s_addc_u32 s79, s79, 0
	global_load_dwordx4 v[216:219], v140, s[78:79] sc0 sc1
	s_waitcnt vmcnt(15)
	v_pk_add_f32 v[84:85], v[84:85], v[220:221]
	v_pk_add_f32 v[86:87], v[86:87], v[222:223]
	s_add_u32 s78, s78, 0x2000
	s_addc_u32 s79, s79, 0
	global_load_dwordx4 v[220:223], v140, s[78:79] sc0 sc1
	s_waitcnt vmcnt(15)
	v_pk_add_f32 v[88:89], v[88:89], v[224:225]
	v_pk_add_f32 v[90:91], v[90:91], v[226:227]
	s_add_u32 s78, s78, 0x2000
	s_addc_u32 s79, s79, 0
	global_load_dwordx4 v[224:227], v140, s[78:79] sc0 sc1
	s_waitcnt vmcnt(15)
	v_pk_add_f32 v[92:93], v[92:93], v[228:229]
	v_pk_add_f32 v[94:95], v[94:95], v[230:231]
	s_add_u32 s78, s78, 0x2000
	s_addc_u32 s79, s79, 0
	global_load_dwordx4 v[228:231], v140, s[78:79] sc0 sc1
	s_waitcnt vmcnt(15)
	v_pk_add_f32 v[96:97], v[96:97], v[232:233]
	v_pk_add_f32 v[98:99], v[98:99], v[234:235]
	s_add_u32 s78, s78, 0x2000
	s_addc_u32 s79, s79, 0
	global_load_dwordx4 v[232:235], v140, s[78:79] sc0 sc1
	s_waitcnt vmcnt(15)
	v_pk_add_f32 v[100:101], v[100:101], v[236:237]
	v_pk_add_f32 v[102:103], v[102:103], v[238:239]
	s_add_u32 s78, s78, 0x2000
	s_addc_u32 s79, s79, 0
	global_load_dwordx4 v[236:239], v140, s[78:79] sc0 sc1
	s_waitcnt vmcnt(15)
	v_pk_add_f32 v[104:105], v[104:105], v[240:241]
	v_pk_add_f32 v[106:107], v[106:107], v[242:243]
	s_add_u32 s78, s78, 0x2000
	s_addc_u32 s79, s79, 0
	global_load_dwordx4 v[240:243], v140, s[78:79] sc0 sc1
	s_waitcnt vmcnt(15)
	v_pk_add_f32 v[108:109], v[108:109], v[244:245]
	v_pk_add_f32 v[110:111], v[110:111], v[246:247]
	s_add_u32 s78, s78, 0x2000
	s_addc_u32 s79, s79, 0
	global_load_dwordx4 v[244:247], v140, s[78:79] sc0 sc1
	s_waitcnt vmcnt(15)
	v_pk_add_f32 v[112:113], v[112:113], v[160:161]
	v_pk_add_f32 v[114:115], v[114:115], v[162:163]
	s_add_u32 s78, s78, 0x2000
	s_addc_u32 s79, s79, 0
	global_load_dwordx4 v[160:163], v140, s[78:79] sc0 sc1
	s_waitcnt vmcnt(15)
	v_pk_add_f32 v[116:117], v[116:117], v[164:165]
	v_pk_add_f32 v[118:119], v[118:119], v[166:167]
	s_add_u32 s78, s78, 0x2000
	s_addc_u32 s79, s79, 0
	global_load_dwordx4 v[164:167], v140, s[78:79] sc0 sc1
	s_waitcnt vmcnt(15)
	v_pk_add_f32 v[120:121], v[120:121], v[168:169]
	v_pk_add_f32 v[122:123], v[122:123], v[170:171]
	s_add_u32 s78, s78, 0x2000
	s_addc_u32 s79, s79, 0
	global_load_dwordx4 v[168:171], v140, s[78:79] sc0 sc1
	s_waitcnt vmcnt(15)
	v_pk_add_f32 v[124:125], v[124:125], v[172:173]
	v_pk_add_f32 v[126:127], v[126:127], v[174:175]
	s_add_u32 s78, s78, 0x2000
	s_addc_u32 s79, s79, 0
	global_load_dwordx4 v[172:175], v140, s[78:79] sc0 sc1
	s_waitcnt vmcnt(15)
	v_pk_add_f32 v[0:1], v[0:1], v[200:201]
	v_pk_add_f32 v[2:3], v[2:3], v[202:203]
	s_add_u32 s78, s78, 0x2000
	s_addc_u32 s79, s79, 0
	global_load_dwordx4 v[200:203], v140, s[78:79] sc0 sc1
	s_waitcnt vmcnt(15)
; template <int l>
; __device__ __forceinline__ void run_layer(LAS unsigned char* lds, unsigned char* ws_in, float* out_in, const float* x_p, const float* x_s, const PIn* pin, const int G, const int bid, const int wave) {
;     ...
;             pg8::RowOrder<DM / 256> S; S.init(G, bid);
;             EpiRes E{ws, out, nullptr, nullptr, 0, -1};
;             pg8::gemm_phase<FF, EpiRes, pg8::RowOrder<DM / 256>>(lds, ACT, (const bf16*)(wb + W_D), S, E, wave);
	v_pk_add_f32 v[4:5], v[4:5], v[204:205]
	v_pk_add_f32 v[6:7], v[6:7], v[206:207]
	s_add_u32 s78, s78, 0x2000
	s_addc_u32 s79, s79, 0
	global_load_dwordx4 v[204:207], v140, s[78:79] sc0 sc1
	s_waitcnt vmcnt(15)
	v_pk_add_f32 v[8:9], v[8:9], v[208:209]
	v_pk_add_f32 v[10:11], v[10:11], v[210:211]
	s_add_u32 s78, s78, 0x2000
	s_addc_u32 s79, s79, 0
	global_load_dwordx4 v[208:211], v140, s[78:79] sc0 sc1
	s_waitcnt vmcnt(15)
	v_pk_add_f32 v[12:13], v[12:13], v[212:213]
	v_pk_add_f32 v[14:15], v[14:15], v[214:215]
	s_add_u32 s78, s78, 0x2000
	s_addc_u32 s79, s79, 0
	global_load_dwordx4 v[212:215], v140, s[78:79] sc0 sc1
	s_waitcnt vmcnt(15)
	v_pk_add_f32 v[16:17], v[16:17], v[216:217]
	v_pk_add_f32 v[18:19], v[18:19], v[218:219]
	s_add_u32 s78, s78, 0x2000
	s_addc_u32 s79, s79, 0
	global_load_dwordx4 v[216:219], v140, s[78:79] sc0 sc1
	s_waitcnt vmcnt(15)
	v_pk_add_f32 v[20:21], v[20:21], v[220:221]
	v_pk_add_f32 v[22:23], v[22:23], v[222:223]
	s_add_u32 s78, s78, 0x2000
	s_addc_u32 s79, s79, 0
	global_load_dwordx4 v[220:223], v140, s[78:79] sc0 sc1
	s_waitcnt vmcnt(15)
	v_pk_add_f32 v[24:25], v[24:25], v[224:225]
	v_pk_add_f32 v[26:27], v[26:27], v[226:227]
	s_add_u32 s78, s78, 0x2000
	s_addc_u32 s79, s79, 0
	global_load_dwordx4 v[224:227], v140, s[78:79] sc0 sc1
	s_waitcnt vmcnt(15)
	v_pk_add_f32 v[28:29], v[28:29], v[228:229]
	v_pk_add_f32 v[30:31], v[30:31], v[230:231]
	s_add_u32 s78, s78, 0x2000
	s_addc_u32 s79, s79, 0
	global_load_dwordx4 v[228:231], v140, s[78:79] sc0 sc1
	s_waitcnt vmcnt(15)
	v_pk_add_f32 v[32:33], v[32:33], v[232:233]
	v_pk_add_f32 v[34:35], v[34:35], v[234:235]
	s_add_u32 s78, s78, 0x2000
	s_addc_u32 s79, s79, 0
	global_load_dwordx4 v[232:235], v140, s[78:79] sc0 sc1
	s_waitcnt vmcnt(15)
	v_pk_add_f32 v[36:37], v[36:37], v[236:237]
	v_pk_add_f32 v[38:39], v[38:39], v[238:239]
	s_add_u32 s78, s78, 0x2000
	s_addc_u32 s79, s79, 0
	global_load_dwordx4 v[236:239], v140, s[78:79] sc0 sc1
	s_waitcnt vmcnt(15)
	v_pk_add_f32 v[40:41], v[40:41], v[240:241]
	v_pk_add_f32 v[42:43], v[42:43], v[242:243]
	s_add_u32 s78, s78, 0x2000
	s_addc_u32 s79, s79, 0
	global_load_dwordx4 v[240:243], v140, s[78:79] sc0 sc1
	s_waitcnt vmcnt(15)
	v_pk_add_f32 v[44:45], v[44:45], v[244:245]
	v_pk_add_f32 v[46:47], v[46:47], v[246:247]
	s_add_u32 s78, s78, 0x2000
	s_addc_u32 s79, s79, 0
	global_load_dwordx4 v[244:247], v140, s[78:79] sc0 sc1
	s_waitcnt vmcnt(15)
	v_pk_add_f32 v[48:49], v[48:49], v[160:161]
	v_pk_add_f32 v[50:51], v[50:51], v[162:163]
	s_add_u32 s78, s78, 0x2000
	s_addc_u32 s79, s79, 0
	global_load_dwordx4 v[160:163], v140, s[78:79] sc0 sc1
	s_waitcnt vmcnt(15)
	v_pk_add_f32 v[52:53], v[52:53], v[164:165]
	v_pk_add_f32 v[54:55], v[54:55], v[166:167]
	s_add_u32 s78, s78, 0x2000
	s_addc_u32 s79, s79, 0
	global_load_dwordx4 v[164:167], v140, s[78:79] sc0 sc1
	s_waitcnt vmcnt(15)
	v_pk_add_f32 v[56:57], v[56:57], v[168:169]
	v_pk_add_f32 v[58:59], v[58:59], v[170:171]
	s_add_u32 s78, s78, 0x2000
	s_addc_u32 s79, s79, 0
	global_load_dwordx4 v[168:171], v140, s[78:79] sc0 sc1
	s_waitcnt vmcnt(15)
	v_pk_add_f32 v[60:61], v[60:61], v[172:173]
	v_pk_add_f32 v[62:63], v[62:63], v[174:175]
	s_add_u32 s78, s78, 0x2000
	s_addc_u32 s79, s79, 0
	global_load_dwordx4 v[172:175], v140, s[78:79] sc0 sc1
	s_waitcnt vmcnt(15)
	v_pk_add_f32 v[64:65], v[64:65], v[200:201]
	v_pk_add_f32 v[66:67], v[66:67], v[202:203]
	s_waitcnt vmcnt(14)
	v_pk_add_f32 v[68:69], v[68:69], v[204:205]
	v_pk_add_f32 v[70:71], v[70:71], v[206:207]
	s_waitcnt vmcnt(13)
	v_pk_add_f32 v[72:73], v[72:73], v[208:209]
	v_pk_add_f32 v[74:75], v[74:75], v[210:211]
	s_waitcnt vmcnt(12)
	v_pk_add_f32 v[76:77], v[76:77], v[212:213]
	v_pk_add_f32 v[78:79], v[78:79], v[214:215]
	s_waitcnt vmcnt(11)
	v_pk_add_f32 v[80:81], v[80:81], v[216:217]
	v_pk_add_f32 v[82:83], v[82:83], v[218:219]
	s_waitcnt vmcnt(10)
	v_pk_add_f32 v[84:85], v[84:85], v[220:221]
	v_pk_add_f32 v[86:87], v[86:87], v[222:223]
	s_waitcnt vmcnt(9)
	v_pk_add_f32 v[88:89], v[88:89], v[224:225]
	v_pk_add_f32 v[90:91], v[90:91], v[226:227]
	s_waitcnt vmcnt(8)
	v_pk_add_f32 v[92:93], v[92:93], v[228:229]
	v_pk_add_f32 v[94:95], v[94:95], v[230:231]
	s_waitcnt vmcnt(7)
	v_pk_add_f32 v[96:97], v[96:97], v[232:233]
	v_pk_add_f32 v[98:99], v[98:99], v[234:235]
	s_waitcnt vmcnt(6)
	v_pk_add_f32 v[100:101], v[100:101], v[236:237]
	v_pk_add_f32 v[102:103], v[102:103], v[238:239]
	s_waitcnt vmcnt(5)
	v_pk_add_f32 v[104:105], v[104:105], v[240:241]
	v_pk_add_f32 v[106:107], v[106:107], v[242:243]
	s_waitcnt vmcnt(4)
	v_pk_add_f32 v[108:109], v[108:109], v[244:245]
	v_pk_add_f32 v[110:111], v[110:111], v[246:247]
	s_waitcnt vmcnt(3)
	v_pk_add_f32 v[112:113], v[112:113], v[160:161]
	v_pk_add_f32 v[114:115], v[114:115], v[162:163]
	s_waitcnt vmcnt(2)
	v_pk_add_f32 v[116:117], v[116:117], v[164:165]
	v_pk_add_f32 v[118:119], v[118:119], v[166:167]
	s_waitcnt vmcnt(1)
	v_pk_add_f32 v[120:121], v[120:121], v[168:169]
	v_pk_add_f32 v[122:123], v[122:123], v[170:171]
	s_waitcnt vmcnt(0)
	v_pk_add_f32 v[124:125], v[124:125], v[172:173]
	v_pk_add_f32 v[126:127], v[126:127], v[174:175]

; template <int l>
; __device__ __forceinline__ void run_layer(LAS unsigned char* lds, unsigned char* ws_in, float* out_in, const float* x_p, const float* x_s, const PIn* pin, const int G, const int bid, const int wave) {
;     ...
;             pg8::RowOrder<DM / 256> S; S.init(G, bid);
;             EpiRes E{ws, out, nullptr, nullptr, 0, -1};
;             pg8::gemm_phase<FF, EpiRes, pg8::RowOrder<DM / 256>>(lds, ACT, (const bf16*)(wb + W_D), S, E, wave);
.Lp5b_go2:
.Lp5b_poll3:
	global_load_dword v142, v141, s[20:21] offset:3212 sc1
	s_waitcnt vmcnt(0)
	v_readfirstlane_b32 s69, v142
	s_nop 0
	s_cmp_ge_u32 s69, 16
	s_cbranch_scc1 .Lp5b_go3
	s_sleep 1
	s_branch .Lp5b_poll3
.Lp5b_go3:
.Lp5b_poll1:
	global_load_dword v142, v141, s[20:21] offset:3204 sc1
	s_waitcnt vmcnt(0)
	v_readfirstlane_b32 s69, v142
	s_nop 0
	s_cmp_ge_u32 s69, 16
	s_cbranch_scc1 .Lp5b_go1
	s_sleep 1
	s_branch .Lp5b_poll1
.Lp5b_go1:
	s_add_u32 s72, s70, 0x40000
	s_addc_u32 s73, s71, 0
	global_load_dwordx4 v[200:203], v140, s[72:73] sc0 sc1
	s_add_u32 s72, s72, 0x2000
	s_addc_u32 s73, s73, 0
	global_load_dwordx4 v[204:207], v140, s[72:73] sc0 sc1
	s_add_u32 s72, s72, 0x2000
	s_addc_u32 s73, s73, 0
	global_load_dwordx4 v[208:211], v140, s[72:73] sc0 sc1
	s_add_u32 s72, s72, 0x2000
	s_addc_u32 s73, s73, 0
	global_load_dwordx4 v[212:215], v140, s[72:73] sc0 sc1
	s_add_u32 s72, s72, 0x2000
	s_addc_u32 s73, s73, 0
	global_load_dwordx4 v[216:219], v140, s[72:73] sc0 sc1
	s_add_u32 s72, s72, 0x2000
	s_addc_u32 s73, s73, 0
	global_load_dwordx4 v[220:223], v140, s[72:73] sc0 sc1
	s_add_u32 s72, s72, 0x2000
	s_addc_u32 s73, s73, 0
	global_load_dwordx4 v[224:227], v140, s[72:73] sc0 sc1
	s_add_u32 s72, s72, 0x2000
	s_addc_u32 s73, s73, 0
	global_load_dwordx4 v[228:231], v140, s[72:73] sc0 sc1
	s_add_u32 s72, s72, 0x2000
	s_addc_u32 s73, s73, 0
	global_load_dwordx4 v[232:235], v140, s[72:73] sc0 sc1
	s_add_u32 s72, s72, 0x2000
	s_addc_u32 s73, s73, 0
	global_load_dwordx4 v[236:239], v140, s[72:73] sc0 sc1
	s_add_u32 s72, s72, 0x2000
	s_addc_u32 s73, s73, 0
	global_load_dwordx4 v[240:243], v140, s[72:73] sc0 sc1
	s_add_u32 s72, s72, 0x2000
	s_addc_u32 s73, s73, 0
	global_load_dwordx4 v[244:247], v140, s[72:73] sc0 sc1
	s_add_u32 s72, s72, 0x2000
	s_addc_u32 s73, s73, 0
	global_load_dwordx4 v[160:163], v140, s[72:73] sc0 sc1
	s_add_u32 s72, s72, 0x2000
	s_addc_u32 s73, s73, 0
	global_load_dwordx4 v[164:167], v140, s[72:73] sc0 sc1
	s_add_u32 s72, s72, 0x2000
	s_addc_u32 s73, s73, 0
	global_load_dwordx4 v[168:171], v140, s[72:73] sc0 sc1
	s_add_u32 s72, s72, 0x2000
	s_addc_u32 s73, s73, 0
	global_load_dwordx4 v[172:175], v140, s[72:73] sc0 sc1
	s_waitcnt vmcnt(15)
	v_pk_add_f32 v[0:1], v[0:1], v[200:201]
	v_pk_add_f32 v[2:3], v[2:3], v[202:203]
	s_add_u32 s72, s72, 0x2000
	s_addc_u32 s73, s73, 0
	global_load_dwordx4 v[200:203], v140, s[72:73] sc0 sc1
	s_waitcnt vmcnt(15)
	v_pk_add_f32 v[4:5], v[4:5], v[204:205]
	v_pk_add_f32 v[6:7], v[6:7], v[206:207]
	s_add_u32 s72, s72, 0x2000
	s_addc_u32 s73, s73, 0
	global_load_dwordx4 v[204:207], v140, s[72:73] sc0 sc1
	s_waitcnt vmcnt(15)
	v_pk_add_f32 v[8:9], v[8:9], v[208:209]
	v_pk_add_f32 v[10:11], v[10:11], v[210:211]
	s_add_u32 s72, s72, 0x2000
	s_addc_u32 s73, s73, 0
	global_load_dwordx4 v[208:211], v140, s[72:73] sc0 sc1
	s_waitcnt vmcnt(15)
	v_pk_add_f32 v[12:13], v[12:13], v[212:213]
	v_pk_add_f32 v[14:15], v[14:15], v[214:215]
	s_add_u32 s72, s72, 0x2000
	s_addc_u32 s73, s73, 0
	global_load_dwordx4 v[212:215], v140, s[72:73] sc0 sc1
	s_waitcnt vmcnt(15)
	v_pk_add_f32 v[16:17], v[16:17], v[216:217]
	v_pk_add_f32 v[18:19], v[18:19], v[218:219]
	s_add_u32 s72, s72, 0x2000
	s_addc_u32 s73, s73, 0
	global_load_dwordx4 v[216:219], v140, s[72:73] sc0 sc1
	s_waitcnt vmcnt(15)
	v_pk_add_f32 v[20:21], v[20:21], v[220:221]
	v_pk_add_f32 v[22:23], v[22:23], v[222:223]
	s_add_u32 s72, s72, 0x2000
	s_addc_u32 s73, s73, 0
	global_load_dwordx4 v[220:223], v140, s[72:73] sc0 sc1
	s_waitcnt vmcnt(15)
	v_pk_add_f32 v[24:25], v[24:25], v[224:225]
	v_pk_add_f32 v[26:27], v[26:27], v[226:227]
	s_add_u32 s72, s72, 0x2000
	s_addc_u32 s73, s73, 0
	global_load_dwordx4 v[224:227], v140, s[72:73] sc0 sc1
	s_waitcnt vmcnt(15)
	v_pk_add_f32 v[28:29], v[28:29], v[228:229]
	v_pk_add_f32 v[30:31], v[30:31], v[230:231]
	s_add_u32 s72, s72, 0x2000
	s_addc_u32 s73, s73, 0
	global_load_dwordx4 v[228:231], v140, s[72:73] sc0 sc1
	s_waitcnt vmcnt(15)
	v_pk_add_f32 v[32:33], v[32:33], v[232:233]
	v_pk_add_f32 v[34:35], v[34:35], v[234:235]
	s_add_u32 s72, s72, 0x2000
	s_addc_u32 s73, s73, 0
	global_load_dwordx4 v[232:235], v140, s[72:73] sc0 sc1
	s_waitcnt vmcnt(15)
	v_pk_add_f32 v[36:37], v[36:37], v[236:237]
	v_pk_add_f32 v[38:39], v[38:39], v[238:239]
	s_add_u32 s72, s72, 0x2000
	s_addc_u32 s73, s73, 0
	global_load_dwordx4 v[236:239], v140, s[72:73] sc0 sc1
	s_waitcnt vmcnt(15)
	v_pk_add_f32 v[40:41], v[40:41], v[240:241]
	v_pk_add_f32 v[42:43], v[42:43], v[242:243]
	s_add_u32 s72, s72, 0x2000
	s_addc_u32 s73, s73, 0
	global_load_dwordx4 v[240:243], v140, s[72:73] sc0 sc1
	s_waitcnt vmcnt(15)
	v_pk_add_f32 v[44:45], v[44:45], v[244:245]
	v_pk_add_f32 v[46:47], v[46:47], v[246:247]
	s_add_u32 s72, s72, 0x2000
	s_addc_u32 s73, s73, 0
	global_load_dwordx4 v[244:247], v140, s[72:73] sc0 sc1
	s_waitcnt vmcnt(15)
	v_pk_add_f32 v[48:49], v[48:49], v[160:161]
	v_pk_add_f32 v[50:51], v[50:51], v[162:163]
	s_add_u32 s72, s72, 0x2000
	s_addc_u32 s73, s73, 0
	global_load_dwordx4 v[160:163], v140, s[72:73] sc0 sc1
	s_waitcnt vmcnt(15)
	v_pk_add_f32 v[52:53], v[52:53], v[164:165]
	v_pk_add_f32 v[54:55], v[54:55], v[166:167]
	s_add_u32 s72, s72, 0x2000
	s_addc_u32 s73, s73, 0
	global_load_dwordx4 v[164:167], v140, s[72:73] sc0 sc1
	s_waitcnt vmcnt(15)
	v_pk_add_f32 v[56:57], v[56:57], v[168:169]
	v_pk_add_f32 v[58:59], v[58:59], v[170:171]
	s_add_u32 s72, s72, 0x2000
	s_addc_u32 s73, s73, 0
	global_load_dwordx4 v[168:171], v140, s[72:73] sc0 sc1
	s_waitcnt vmcnt(15)
	v_pk_add_f32 v[60:61], v[60:61], v[172:173]
	v_pk_add_f32 v[62:63], v[62:63], v[174:175]
	s_add_u32 s72, s72, 0x2000
	s_addc_u32 s73, s73, 0
	global_load_dwordx4 v[172:175], v140, s[72:73] sc0 sc1
	s_waitcnt vmcnt(15)
; template <int l>
; __device__ __forceinline__ void run_layer(LAS unsigned char* lds, unsigned char* ws_in, float* out_in, const float* x_p, const float* x_s, const PIn* pin, const int G, const int bid, const int wave) {
;     ...
;             pg8::RowOrder<DM / 256> S; S.init(G, bid);
;             EpiRes E{ws, out, nullptr, nullptr, 0, -1};
;             pg8::gemm_phase<FF, EpiRes, pg8::RowOrder<DM / 256>>(lds, ACT, (const bf16*)(wb + W_D), S, E, wave);
	v_pk_add_f32 v[64:65], v[64:65], v[200:201]
	v_pk_add_f32 v[66:67], v[66:67], v[202:203]
	s_add_u32 s72, s70, 0x80000
	s_addc_u32 s73, s71, 0
	global_load_dwordx4 v[200:203], v140, s[72:73] sc0 sc1
	s_waitcnt vmcnt(15)
	v_pk_add_f32 v[68:69], v[68:69], v[204:205]
	v_pk_add_f32 v[70:71], v[70:71], v[206:207]
	s_add_u32 s72, s72, 0x2000
	s_addc_u32 s73, s73, 0
	global_load_dwordx4 v[204:207], v140, s[72:73] sc0 sc1
	s_waitcnt vmcnt(15)
	v_pk_add_f32 v[72:73], v[72:73], v[208:209]
	v_pk_add_f32 v[74:75], v[74:75], v[210:211]
	s_add_u32 s72, s72, 0x2000
	s_addc_u32 s73, s73, 0
	global_load_dwordx4 v[208:211], v140, s[72:73] sc0 sc1
	s_waitcnt vmcnt(15)
	v_pk_add_f32 v[76:77], v[76:77], v[212:213]
	v_pk_add_f32 v[78:79], v[78:79], v[214:215]
	s_add_u32 s72, s72, 0x2000
	s_addc_u32 s73, s73, 0
	global_load_dwordx4 v[212:215], v140, s[72:73] sc0 sc1
	s_waitcnt vmcnt(15)
	v_pk_add_f32 v[80:81], v[80:81], v[216:217]
	v_pk_add_f32 v[82:83], v[82:83], v[218:219]
	s_add_u32 s72, s72, 0x2000
	s_addc_u32 s73, s73, 0
	global_load_dwordx4 v[216:219], v140, s[72:73] sc0 sc1
	s_waitcnt vmcnt(15)
	v_pk_add_f32 v[84:85], v[84:85], v[220:221]
	v_pk_add_f32 v[86:87], v[86:87], v[222:223]
	s_add_u32 s72, s72, 0x2000
	s_addc_u32 s73, s73, 0
	global_load_dwordx4 v[220:223], v140, s[72:73] sc0 sc1
	s_waitcnt vmcnt(15)
	v_pk_add_f32 v[88:89], v[88:89], v[224:225]
	v_pk_add_f32 v[90:91], v[90:91], v[226:227]
	s_add_u32 s72, s72, 0x2000
	s_addc_u32 s73, s73, 0
	global_load_dwordx4 v[224:227], v140, s[72:73] sc0 sc1
	s_waitcnt vmcnt(15)
	v_pk_add_f32 v[92:93], v[92:93], v[228:229]
	v_pk_add_f32 v[94:95], v[94:95], v[230:231]
	s_add_u32 s72, s72, 0x2000
	s_addc_u32 s73, s73, 0
	global_load_dwordx4 v[228:231], v140, s[72:73] sc0 sc1
	s_waitcnt vmcnt(15)
	v_pk_add_f32 v[96:97], v[96:97], v[232:233]
	v_pk_add_f32 v[98:99], v[98:99], v[234:235]
	s_add_u32 s72, s72, 0x2000
	s_addc_u32 s73, s73, 0
	global_load_dwordx4 v[232:235], v140, s[72:73] sc0 sc1
	s_waitcnt vmcnt(15)
	v_pk_add_f32 v[100:101], v[100:101], v[236:237]
	v_pk_add_f32 v[102:103], v[102:103], v[238:239]
	s_add_u32 s72, s72, 0x2000
	s_addc_u32 s73, s73, 0
	global_load_dwordx4 v[236:239], v140, s[72:73] sc0 sc1
	s_waitcnt vmcnt(15)
	v_pk_add_f32 v[104:105], v[104:105], v[240:241]
	v_pk_add_f32 v[106:107], v[106:107], v[242:243]
	s_add_u32 s72, s72, 0x2000
	s_addc_u32 s73, s73, 0
	global_load_dwordx4 v[240:243], v140, s[72:73] sc0 sc1
	s_waitcnt vmcnt(15)
	v_pk_add_f32 v[108:109], v[108:109], v[244:245]
	v_pk_add_f32 v[110:111], v[110:111], v[246:247]
	s_add_u32 s72, s72, 0x2000
	s_addc_u32 s73, s73, 0
	global_load_dwordx4 v[244:247], v140, s[72:73] sc0 sc1
	s_waitcnt vmcnt(15)
	v_pk_add_f32 v[112:113], v[112:113], v[160:161]
	v_pk_add_f32 v[114:115], v[114:115], v[162:163]
	s_add_u32 s72, s72, 0x2000
	s_addc_u32 s73, s73, 0
	global_load_dwordx4 v[160:163], v140, s[72:73] sc0 sc1
	s_waitcnt vmcnt(15)
	v_pk_add_f32 v[116:117], v[116:117], v[164:165]
	v_pk_add_f32 v[118:119], v[118:119], v[166:167]
	s_add_u32 s72, s72, 0x2000
	s_addc_u32 s73, s73, 0
	global_load_dwordx4 v[164:167], v140, s[72:73] sc0 sc1
	s_waitcnt vmcnt(15)
	v_pk_add_f32 v[120:121], v[120:121], v[168:169]
	v_pk_add_f32 v[122:123], v[122:123], v[170:171]
	s_add_u32 s72, s72, 0x2000
	s_addc_u32 s73, s73, 0
	global_load_dwordx4 v[168:171], v140, s[72:73] sc0 sc1
	s_waitcnt vmcnt(15)
	v_pk_add_f32 v[124:125], v[124:125], v[172:173]
	v_pk_add_f32 v[126:127], v[126:127], v[174:175]
	s_add_u32 s72, s72, 0x2000
	s_addc_u32 s73, s73, 0
	global_load_dwordx4 v[172:175], v140, s[72:73] sc0 sc1
	s_waitcnt vmcnt(15)
	v_pk_add_f32 v[0:1], v[0:1], v[200:201]
	v_pk_add_f32 v[2:3], v[2:3], v[202:203]
	s_add_u32 s72, s72, 0x2000
	s_addc_u32 s73, s73, 0
	global_load_dwordx4 v[200:203], v140, s[72:73] sc0 sc1
	s_waitcnt vmcnt(15)
	v_pk_add_f32 v[4:5], v[4:5], v[204:205]
	v_pk_add_f32 v[6:7], v[6:7], v[206:207]
	s_add_u32 s72, s72, 0x2000
	s_addc_u32 s73, s73, 0
	global_load_dwordx4 v[204:207], v140, s[72:73] sc0 sc1
	s_waitcnt vmcnt(15)
	v_pk_add_f32 v[8:9], v[8:9], v[208:209]
	v_pk_add_f32 v[10:11], v[10:11], v[210:211]
	s_add_u32 s72, s72, 0x2000
	s_addc_u32 s73, s73, 0
	global_load_dwordx4 v[208:211], v140, s[72:73] sc0 sc1
	s_waitcnt vmcnt(15)
	v_pk_add_f32 v[12:13], v[12:13], v[212:213]
	v_pk_add_f32 v[14:15], v[14:15], v[214:215]
	s_add_u32 s72, s72, 0x2000
	s_addc_u32 s73, s73, 0
	global_load_dwordx4 v[212:215], v140, s[72:73] sc0 sc1
	s_waitcnt vmcnt(15)
	v_pk_add_f32 v[16:17], v[16:17], v[216:217]
	v_pk_add_f32 v[18:19], v[18:19], v[218:219]
	s_add_u32 s72, s72, 0x2000
	s_addc_u32 s73, s73, 0
	global_load_dwordx4 v[216:219], v140, s[72:73] sc0 sc1
	s_waitcnt vmcnt(15)
	v_pk_add_f32 v[20:21], v[20:21], v[220:221]
	v_pk_add_f32 v[22:23], v[22:23], v[222:223]
	s_add_u32 s72, s72, 0x2000
	s_addc_u32 s73, s73, 0
	global_load_dwordx4 v[220:223], v140, s[72:73] sc0 sc1
	s_waitcnt vmcnt(15)
	v_pk_add_f32 v[24:25], v[24:25], v[224:225]
	v_pk_add_f32 v[26:27], v[26:27], v[226:227]
	s_add_u32 s72, s72, 0x2000
	s_addc_u32 s73, s73, 0
	global_load_dwordx4 v[224:227], v140, s[72:73] sc0 sc1
	s_waitcnt vmcnt(15)
	v_pk_add_f32 v[28:29], v[28:29], v[228:229]
	v_pk_add_f32 v[30:31], v[30:31], v[230:231]
	s_add_u32 s72, s72, 0x2000
	s_addc_u32 s73, s73, 0
	global_load_dwordx4 v[228:231], v140, s[72:73] sc0 sc1
	s_waitcnt vmcnt(15)
	v_pk_add_f32 v[32:33], v[32:33], v[232:233]
	v_pk_add_f32 v[34:35], v[34:35], v[234:235]
	s_add_u32 s72, s72, 0x2000
	s_addc_u32 s73, s73, 0
	global_load_dwordx4 v[232:235], v140, s[72:73] sc0 sc1
	s_waitcnt vmcnt(15)
	v_pk_add_f32 v[36:37], v[36:37], v[236:237]
	v_pk_add_f32 v[38:39], v[38:39], v[238:239]
	s_add_u32 s72, s72, 0x2000
	s_addc_u32 s73, s73, 0
	global_load_dwordx4 v[236:239], v140, s[72:73] sc0 sc1
	s_waitcnt vmcnt(15)
; template <int l>
; __device__ __forceinline__ void run_layer(LAS unsigned char* lds, unsigned char* ws_in, float* out_in, const float* x_p, const float* x_s, const PIn* pin, const int G, const int bid, const int wave) {
;     ...
;             pg8::RowOrder<DM / 256> S; S.init(G, bid);
;             EpiRes E{ws, out, nullptr, nullptr, 0, -1};
;             pg8::gemm_phase<FF, EpiRes, pg8::RowOrder<DM / 256>>(lds, ACT, (const bf16*)(wb + W_D), S, E, wave);
	v_pk_add_f32 v[40:41], v[40:41], v[240:241]
	v_pk_add_f32 v[42:43], v[42:43], v[242:243]
	s_add_u32 s72, s72, 0x2000
	s_addc_u32 s73, s73, 0
	global_load_dwordx4 v[240:243], v140, s[72:73] sc0 sc1
	s_waitcnt vmcnt(15)
	v_pk_add_f32 v[44:45], v[44:45], v[244:245]
	v_pk_add_f32 v[46:47], v[46:47], v[246:247]
	s_add_u32 s72, s72, 0x2000
	s_addc_u32 s73, s73, 0
	global_load_dwordx4 v[244:247], v140, s[72:73] sc0 sc1
	s_waitcnt vmcnt(15)
	v_pk_add_f32 v[48:49], v[48:49], v[160:161]
	v_pk_add_f32 v[50:51], v[50:51], v[162:163]
	s_add_u32 s72, s72, 0x2000
	s_addc_u32 s73, s73, 0
	global_load_dwordx4 v[160:163], v140, s[72:73] sc0 sc1
	s_waitcnt vmcnt(15)
	v_pk_add_f32 v[52:53], v[52:53], v[164:165]
	v_pk_add_f32 v[54:55], v[54:55], v[166:167]
	s_add_u32 s72, s72, 0x2000
	s_addc_u32 s73, s73, 0
	global_load_dwordx4 v[164:167], v140, s[72:73] sc0 sc1
	s_waitcnt vmcnt(15)
	v_pk_add_f32 v[56:57], v[56:57], v[168:169]
	v_pk_add_f32 v[58:59], v[58:59], v[170:171]
	s_add_u32 s72, s72, 0x2000
	s_addc_u32 s73, s73, 0
	global_load_dwordx4 v[168:171], v140, s[72:73] sc0 sc1
	s_waitcnt vmcnt(15)
	v_pk_add_f32 v[60:61], v[60:61], v[172:173]
	v_pk_add_f32 v[62:63], v[62:63], v[174:175]
	s_add_u32 s72, s72, 0x2000
	s_addc_u32 s73, s73, 0
	global_load_dwordx4 v[172:175], v140, s[72:73] sc0 sc1
	s_waitcnt vmcnt(15)
	v_pk_add_f32 v[64:65], v[64:65], v[200:201]
	v_pk_add_f32 v[66:67], v[66:67], v[202:203]
	s_add_u32 s72, s70, 0x0
	s_addc_u32 s73, s71, 0
	global_load_dwordx4 v[200:203], v140, s[72:73] sc0 sc1
	s_waitcnt vmcnt(15)
	v_pk_add_f32 v[68:69], v[68:69], v[204:205]
	v_pk_add_f32 v[70:71], v[70:71], v[206:207]
	s_add_u32 s72, s72, 0x2000
	s_addc_u32 s73, s73, 0
	global_load_dwordx4 v[204:207], v140, s[72:73] sc0 sc1
	s_waitcnt vmcnt(15)
	v_pk_add_f32 v[72:73], v[72:73], v[208:209]
	v_pk_add_f32 v[74:75], v[74:75], v[210:211]
	s_add_u32 s72, s72, 0x2000
	s_addc_u32 s73, s73, 0
	global_load_dwordx4 v[208:211], v140, s[72:73] sc0 sc1
	s_waitcnt vmcnt(15)
	v_pk_add_f32 v[76:77], v[76:77], v[212:213]
	v_pk_add_f32 v[78:79], v[78:79], v[214:215]
	s_add_u32 s72, s72, 0x2000
	s_addc_u32 s73, s73, 0
	global_load_dwordx4 v[212:215], v140, s[72:73] sc0 sc1
	s_waitcnt vmcnt(15)
	v_pk_add_f32 v[80:81], v[80:81], v[216:217]
	v_pk_add_f32 v[82:83], v[82:83], v[218:219]
	s_add_u32 s72, s72, 0x2000
	s_addc_u32 s73, s73, 0
	global_load_dwordx4 v[216:219], v140, s[72:73] sc0 sc1
	s_waitcnt vmcnt(15)
	v_pk_add_f32 v[84:85], v[84:85], v[220:221]
	v_pk_add_f32 v[86:87], v[86:87], v[222:223]
	s_add_u32 s72, s72, 0x2000
	s_addc_u32 s73, s73, 0
	global_load_dwordx4 v[220:223], v140, s[72:73] sc0 sc1
	s_waitcnt vmcnt(15)
	v_pk_add_f32 v[88:89], v[88:89], v[224:225]
	v_pk_add_f32 v[90:91], v[90:91], v[226:227]
	s_add_u32 s72, s72, 0x2000
	s_addc_u32 s73, s73, 0
	global_load_dwordx4 v[224:227], v140, s[72:73] sc0 sc1
	s_waitcnt vmcnt(15)
	v_pk_add_f32 v[92:93], v[92:93], v[228:229]
	v_pk_add_f32 v[94:95], v[94:95], v[230:231]
	s_add_u32 s72, s72, 0x2000
	s_addc_u32 s73, s73, 0
	global_load_dwordx4 v[228:231], v140, s[72:73] sc0 sc1
	s_waitcnt vmcnt(15)
	v_pk_add_f32 v[96:97], v[96:97], v[232:233]
	v_pk_add_f32 v[98:99], v[98:99], v[234:235]
	s_add_u32 s72, s72, 0x2000
	s_addc_u32 s73, s73, 0
	global_load_dwordx4 v[232:235], v140, s[72:73] sc0 sc1
	s_waitcnt vmcnt(15)
	v_pk_add_f32 v[100:101], v[100:101], v[236:237]
	v_pk_add_f32 v[102:103], v[102:103], v[238:239]
	s_add_u32 s72, s72, 0x2000
	s_addc_u32 s73, s73, 0
	global_load_dwordx4 v[236:239], v140, s[72:73] sc0 sc1
	s_waitcnt vmcnt(15)
	v_pk_add_f32 v[104:105], v[104:105], v[240:241]
	v_pk_add_f32 v[106:107], v[106:107], v[242:243]
	s_add_u32 s72, s72, 0x2000
	s_addc_u32 s73, s73, 0
	global_load_dwordx4 v[240:243], v140, s[72:73] sc0 sc1
	s_waitcnt vmcnt(15)
	v_pk_add_f32 v[108:109], v[108:109], v[244:245]
	v_pk_add_f32 v[110:111], v[110:111], v[246:247]
	s_add_u32 s72, s72, 0x2000
	s_addc_u32 s73, s73, 0
	global_load_dwordx4 v[244:247], v140, s[72:73] sc0 sc1
	s_waitcnt vmcnt(15)
	v_pk_add_f32 v[112:113], v[112:113], v[160:161]
	v_pk_add_f32 v[114:115], v[114:115], v[162:163]
	s_add_u32 s72, s72, 0x2000
	s_addc_u32 s73, s73, 0
	global_load_dwordx4 v[160:163], v140, s[72:73] sc0 sc1
	s_waitcnt vmcnt(15)
	v_pk_add_f32 v[116:117], v[116:117], v[164:165]
	v_pk_add_f32 v[118:119], v[118:119], v[166:167]
	s_add_u32 s72, s72, 0x2000
	s_addc_u32 s73, s73, 0
	global_load_dwordx4 v[164:167], v140, s[72:73] sc0 sc1
	s_waitcnt vmcnt(15)
	v_pk_add_f32 v[120:121], v[120:121], v[168:169]
	v_pk_add_f32 v[122:123], v[122:123], v[170:171]
	s_add_u32 s72, s72, 0x2000
	s_addc_u32 s73, s73, 0
	global_load_dwordx4 v[168:171], v140, s[72:73] sc0 sc1
	s_waitcnt vmcnt(15)
	v_pk_add_f32 v[124:125], v[124:125], v[172:173]
	v_pk_add_f32 v[126:127], v[126:127], v[174:175]
	s_add_u32 s72, s72, 0x2000
	s_addc_u32 s73, s73, 0
	global_load_dwordx4 v[172:175], v140, s[72:73] sc0 sc1
	s_waitcnt vmcnt(15)
	v_pk_add_f32 v[0:1], v[0:1], v[200:201]
	v_pk_add_f32 v[2:3], v[2:3], v[202:203]
	s_add_u32 s72, s72, 0x2000
	s_addc_u32 s73, s73, 0
	global_load_dwordx4 v[200:203], v140, s[72:73] sc0 sc1
	s_waitcnt vmcnt(15)
; template <int l>
; __device__ __forceinline__ void run_layer(LAS unsigned char* lds, unsigned char* ws_in, float* out_in, const float* x_p, const float* x_s, const PIn* pin, const int G, const int bid, const int wave) {
;     ...
;             pg8::RowOrder<DM / 256> S; S.init(G, bid);
;             EpiRes E{ws, out, nullptr, nullptr, 0, -1};
;             pg8::gemm_phase<FF, EpiRes, pg8::RowOrder<DM / 256>>(lds, ACT, (const bf16*)(wb + W_D), S, E, wave);
	v_pk_add_f32 v[4:5], v[4:5], v[204:205]
	v_pk_add_f32 v[6:7], v[6:7], v[206:207]
	s_add_u32 s72, s72, 0x2000
	s_addc_u32 s73, s73, 0
	global_load_dwordx4 v[204:207], v140, s[72:73] sc0 sc1
	s_waitcnt vmcnt(15)
	v_pk_add_f32 v[8:9], v[8:9], v[208:209]
	v_pk_add_f32 v[10:11], v[10:11], v[210:211]
	s_add_u32 s72, s72, 0x2000
	s_addc_u32 s73, s73, 0
	global_load_dwordx4 v[208:211], v140, s[72:73] sc0 sc1
	s_waitcnt vmcnt(15)
	v_pk_add_f32 v[12:13], v[12:13], v[212:213]
	v_pk_add_f32 v[14:15], v[14:15], v[214:215]
	s_add_u32 s72, s72, 0x2000
	s_addc_u32 s73, s73, 0
	global_load_dwordx4 v[212:215], v140, s[72:73] sc0 sc1
	s_waitcnt vmcnt(15)
	v_pk_add_f32 v[16:17], v[16:17], v[216:217]
	v_pk_add_f32 v[18:19], v[18:19], v[218:219]
	s_add_u32 s72, s72, 0x2000
	s_addc_u32 s73, s73, 0
	global_load_dwordx4 v[216:219], v140, s[72:73] sc0 sc1
	s_waitcnt vmcnt(15)
	v_pk_add_f32 v[20:21], v[20:21], v[220:221]
	v_pk_add_f32 v[22:23], v[22:23], v[222:223]
	s_add_u32 s72, s72, 0x2000
	s_addc_u32 s73, s73, 0
	global_load_dwordx4 v[220:223], v140, s[72:73] sc0 sc1
	s_waitcnt vmcnt(15)
	v_pk_add_f32 v[24:25], v[24:25], v[224:225]
	v_pk_add_f32 v[26:27], v[26:27], v[226:227]
	s_add_u32 s72, s72, 0x2000
	s_addc_u32 s73, s73, 0
	global_load_dwordx4 v[224:227], v140, s[72:73] sc0 sc1
	s_waitcnt vmcnt(15)
	v_pk_add_f32 v[28:29], v[28:29], v[228:229]
	v_pk_add_f32 v[30:31], v[30:31], v[230:231]
	s_add_u32 s72, s72, 0x2000
	s_addc_u32 s73, s73, 0
	global_load_dwordx4 v[228:231], v140, s[72:73] sc0 sc1
	s_waitcnt vmcnt(15)
	v_pk_add_f32 v[32:33], v[32:33], v[232:233]
	v_pk_add_f32 v[34:35], v[34:35], v[234:235]
	s_add_u32 s72, s72, 0x2000
	s_addc_u32 s73, s73, 0
	global_load_dwordx4 v[232:235], v140, s[72:73] sc0 sc1
	s_waitcnt vmcnt(15)
	v_pk_add_f32 v[36:37], v[36:37], v[236:237]
	v_pk_add_f32 v[38:39], v[38:39], v[238:239]
	s_add_u32 s72, s72, 0x2000
	s_addc_u32 s73, s73, 0
	global_load_dwordx4 v[236:239], v140, s[72:73] sc0 sc1
	s_waitcnt vmcnt(15)
	v_pk_add_f32 v[40:41], v[40:41], v[240:241]
	v_pk_add_f32 v[42:43], v[42:43], v[242:243]
	s_add_u32 s72, s72, 0x2000
	s_addc_u32 s73, s73, 0
	global_load_dwordx4 v[240:243], v140, s[72:73] sc0 sc1
	s_waitcnt vmcnt(15)
	v_pk_add_f32 v[44:45], v[44:45], v[244:245]
	v_pk_add_f32 v[46:47], v[46:47], v[246:247]
	s_add_u32 s72, s72, 0x2000
	s_addc_u32 s73, s73, 0
	global_load_dwordx4 v[244:247], v140, s[72:73] sc0 sc1
	s_waitcnt vmcnt(15)
	v_pk_add_f32 v[48:49], v[48:49], v[160:161]
	v_pk_add_f32 v[50:51], v[50:51], v[162:163]
	s_add_u32 s72, s72, 0x2000
	s_addc_u32 s73, s73, 0
	global_load_dwordx4 v[160:163], v140, s[72:73] sc0 sc1
	s_waitcnt vmcnt(15)
	v_pk_add_f32 v[52:53], v[52:53], v[164:165]
	v_pk_add_f32 v[54:55], v[54:55], v[166:167]
	s_add_u32 s72, s72, 0x2000
	s_addc_u32 s73, s73, 0
	global_load_dwordx4 v[164:167], v140, s[72:73] sc0 sc1
	s_waitcnt vmcnt(15)
	v_pk_add_f32 v[56:57], v[56:57], v[168:169]
	v_pk_add_f32 v[58:59], v[58:59], v[170:171]
	s_add_u32 s72, s72, 0x2000
	s_addc_u32 s73, s73, 0
	global_load_dwordx4 v[168:171], v140, s[72:73] sc0 sc1
	s_waitcnt vmcnt(15)
	v_pk_add_f32 v[60:61], v[60:61], v[172:173]
	v_pk_add_f32 v[62:63], v[62:63], v[174:175]
	s_add_u32 s72, s72, 0x2000
	s_addc_u32 s73, s73, 0
	global_load_dwordx4 v[172:175], v140, s[72:73] sc0 sc1
	s_waitcnt vmcnt(15)
	v_pk_add_f32 v[64:65], v[64:65], v[200:201]
	v_pk_add_f32 v[66:67], v[66:67], v[202:203]
	s_waitcnt vmcnt(14)
	v_pk_add_f32 v[68:69], v[68:69], v[204:205]
	v_pk_add_f32 v[70:71], v[70:71], v[206:207]
	s_waitcnt vmcnt(13)
	v_pk_add_f32 v[72:73], v[72:73], v[208:209]
	v_pk_add_f32 v[74:75], v[74:75], v[210:211]
	s_waitcnt vmcnt(12)
	v_pk_add_f32 v[76:77], v[76:77], v[212:213]
	v_pk_add_f32 v[78:79], v[78:79], v[214:215]
	s_waitcnt vmcnt(11)
	v_pk_add_f32 v[80:81], v[80:81], v[216:217]
	v_pk_add_f32 v[82:83], v[82:83], v[218:219]
	s_waitcnt vmcnt(10)
	v_pk_add_f32 v[84:85], v[84:85], v[220:221]
	v_pk_add_f32 v[86:87], v[86:87], v[222:223]
	s_waitcnt vmcnt(9)
	v_pk_add_f32 v[88:89], v[88:89], v[224:225]
	v_pk_add_f32 v[90:91], v[90:91], v[226:227]
	s_waitcnt vmcnt(8)
	v_pk_add_f32 v[92:93], v[92:93], v[228:229]
	v_pk_add_f32 v[94:95], v[94:95], v[230:231]
	s_waitcnt vmcnt(7)
	v_pk_add_f32 v[96:97], v[96:97], v[232:233]
	v_pk_add_f32 v[98:99], v[98:99], v[234:235]
	s_waitcnt vmcnt(6)
	v_pk_add_f32 v[100:101], v[100:101], v[236:237]
	v_pk_add_f32 v[102:103], v[102:103], v[238:239]
	s_waitcnt vmcnt(5)
	v_pk_add_f32 v[104:105], v[104:105], v[240:241]
	v_pk_add_f32 v[106:107], v[106:107], v[242:243]
	s_waitcnt vmcnt(4)
	v_pk_add_f32 v[108:109], v[108:109], v[244:245]
	v_pk_add_f32 v[110:111], v[110:111], v[246:247]
	s_waitcnt vmcnt(3)
	v_pk_add_f32 v[112:113], v[112:113], v[160:161]
	v_pk_add_f32 v[114:115], v[114:115], v[162:163]
	s_waitcnt vmcnt(2)
	v_pk_add_f32 v[116:117], v[116:117], v[164:165]
	v_pk_add_f32 v[118:119], v[118:119], v[166:167]
	s_waitcnt vmcnt(1)
	v_pk_add_f32 v[120:121], v[120:121], v[168:169]
	v_pk_add_f32 v[122:123], v[122:123], v[170:171]
	s_waitcnt vmcnt(0)
	v_pk_add_f32 v[124:125], v[124:125], v[172:173]
	v_pk_add_f32 v[126:127], v[126:127], v[174:175]
